# prep rope cos/sin table loop: two grid-stride items per pass with both position loads in flight, on top of merge counted wait
# speedup vs baseline: 1.0064x; 1.0064x over previous
; __device__ void prep_phase(const Params& p, unsigned char* smem_g) {
;     ...
;     { float* tab = (float*)(ws + OFF_ROPE);
;       for (int e = blockIdx.x * 512 + tid; e < T_TOK * 16; e += gridDim.x * 512) {
;           const int tok = e >> 4, i = e & 15;
;           const float ang = (float)p.pos[tok] * c_invf[i];
;           const double rev = (double)ang * 0.15915494309189535; const float fr = (float)(rev - rint(rev));
;           tab[tok * 32 + i] = __builtin_amdgcn_cosf(fr); tab[tok * 32 + 16 + i] = __builtin_amdgcn_sinf(fr);
;       } }
.LBB0_147:
	v_add_u32_e32 v10, s70, v2
	v_min_i32_e32 v11, 0x3ffff, v10
	v_ashrrev_i32_e32 v4, 4, v2
	v_ashrrev_i32_e32 v12, 4, v11
	v_lshlrev_b32_e32 v6, 2, v4
	v_lshlrev_b32_e32 v13, 2, v12
	global_load_dword v5, v6, s[76:77]
	global_load_dword v14, v13, s[76:77]
	v_lshl_or_b32 v4, v4, 5, v49
	v_lshl_or_b32 v12, v12, 5, v49
	v_lshlrev_b32_e32 v4, 2, v4
	v_lshlrev_b32_e32 v12, 2, v12
	s_mov_b32 s4, 0x40000
	s_waitcnt vmcnt(0)
	v_cvt_f32_i32_e32 v5, v5
	v_mul_f32_e32 v5, v1, v5
	v_cvt_f64_f32_e32 v[6:7], v5
	v_mul_f64 v[8:9], v[6:7], s[44:45]
	v_rndne_f64_e32 v[8:9], v[8:9]
	v_fma_f64 v[6:7], v[6:7], s[44:45], -v[8:9]
	v_cvt_f32_f64_e32 v6, v[6:7]
	v_cos_f32_e32 v7, v6
	v_sin_f32_e32 v6, v6
	s_nop 1
	global_store_dword v4, v7, s[8:9]
	global_store_dword v4, v6, s[8:9] offset:64
	v_cvt_f32_i32_e32 v14, v14
	v_mul_f32_e32 v14, v1, v14
	v_cvt_f64_f32_e32 v[16:17], v14
	v_mul_f64 v[8:9], v[16:17], s[44:45]
	v_rndne_f64_e32 v[8:9], v[8:9]
	v_fma_f64 v[16:17], v[16:17], s[44:45], -v[8:9]
	v_cvt_f32_f64_e32 v16, v[16:17]
	v_cos_f32_e32 v17, v16
	v_sin_f32_e32 v16, v16
	s_mov_b64 s[6:7], exec
	v_cmp_gt_i32_e32 vcc, s4, v10
	s_and_b64 exec, exec, vcc
	global_store_dword v12, v17, s[8:9]
	global_store_dword v12, v16, s[8:9] offset:64
	s_mov_b64 exec, s[6:7]
	v_add_u32_e32 v2, s70, v10
	v_cmp_le_i32_e32 vcc, s4, v2
	s_or_b64 s[2:3], vcc, s[2:3]
	s_andn2_b64 exec, exec, s[2:3]
	s_cbranch_execnz .LBB0_147
